# v89 + p34_plain_safe2 + xb_local35: merged/xmb/SSQ write-back + barriers 3 and 5 released per XCD (run-time verified placement; chip-wide fallback)
# speedup vs baseline: 1.0057x; 1.0057x over previous
.Lxb0_ok:
	s_mov_b32 s32, 0
	v_readlane_b32 s8, v3, 16
	s_bcnt1_i32_b32 s8, s8
	s_cmp_lg_u32 s8, 1
	s_cselect_b32 s8, 1, 0
	s_or_b32 s32, s32, s8
	v_readlane_b32 s8, v3, 17
	s_bcnt1_i32_b32 s8, s8
	s_cmp_lg_u32 s8, 1
	s_cselect_b32 s8, 1, 0
	s_or_b32 s32, s32, s8
	v_readlane_b32 s8, v3, 18
	s_bcnt1_i32_b32 s8, s8
	s_cmp_lg_u32 s8, 1
	s_cselect_b32 s8, 1, 0
	s_or_b32 s32, s32, s8
	v_readlane_b32 s8, v3, 19
	s_bcnt1_i32_b32 s8, s8
	s_cmp_lg_u32 s8, 1
	s_cselect_b32 s8, 1, 0
	s_or_b32 s32, s32, s8
	v_readlane_b32 s8, v3, 20
	s_bcnt1_i32_b32 s8, s8
	s_cmp_lg_u32 s8, 1
	s_cselect_b32 s8, 1, 0
	s_or_b32 s32, s32, s8
	v_readlane_b32 s8, v3, 21
	s_bcnt1_i32_b32 s8, s8
	s_cmp_lg_u32 s8, 1
	s_cselect_b32 s8, 1, 0
	s_or_b32 s32, s32, s8
	v_readlane_b32 s8, v3, 22
	s_bcnt1_i32_b32 s8, s8
	s_cmp_lg_u32 s8, 1
	s_cselect_b32 s8, 1, 0
	s_or_b32 s32, s32, s8
	v_readlane_b32 s8, v3, 23
	s_bcnt1_i32_b32 s8, s8
	s_cmp_lg_u32 s8, 1
	s_cselect_b32 s8, 1, 0
	s_or_b32 s32, s32, s8
	s_cmp_lg_u32 s3, 0x100
	s_cselect_b32 s8, 1, 0
	s_or_b32 s32, s32, s8
	v_writelane_b32 v255, s32, 63
	s_mov_b64 exec, 0xffff
	v_cmp_ne_u32_e32 vcc, 0, v3
	s_nop 3
	v_readlane_b32 s16, v3, s87
	s_bcnt1_i32_b64 s9, vcc
	s_max_u32 s16, s16, 1
	s_max_u32 s9, s9, 1
	s_mov_b64 exec, 1
	v_mov_b32_e32 v1, 0x23ff0
	v_mov_b32_e32 v2, s16
	v_mov_b32_e32 v3, s9
	ds_write_b32 v1, v2
	ds_write_b32 v1, v3 offset:4
	s_waitcnt lgkmcnt(0)
	v_mov_b32_e32 v1, 0x23ff0
	ds_read_b32 v2, v1
	ds_read_b32 v3, v1 offset:4
	s_add_u32 s6, s80, 0x2380000
	s_addc_u32 s7, s81, 0
	s_lshl_b32 s8, s87, 8
	s_add_i32 s9, s8, 0x1400
	s_add_i32 s8, s8, 0x2400
	v_mov_b32_e32 v4, s9
	v_mov_b32_e32 v5, 1
	global_atomic_add v6, v4, v5, s[6:7] sc0
	buffer_inv sc1
	s_waitcnt vmcnt(0) lgkmcnt(0)
	v_readfirstlane_b32 s10, v6
	v_readfirstlane_b32 s11, v2
	v_readfirstlane_b32 s16, v3
	s_add_i32 s10, s10, 1
	s_mul_i32 s11, s11, 1
	s_cmp_lg_u32 s10, s11
	s_cbranch_scc1 .Lxb_nl_0
	buffer_wbl2 sc1
	s_waitcnt vmcnt(0)
	v_mov_b32_e32 v4, 0x3400
	global_atomic_add v6, v4, v5, s[6:7] sc0
	s_waitcnt vmcnt(0)
	v_readfirstlane_b32 s10, v6
	s_add_i32 s10, s10, 1
	s_mul_i32 s16, s16, 1
	s_cmp_lg_u32 s10, s16
	s_cbranch_scc1 .Lxb_nl_0
	v_mov_b32_e32 v4, 0x2400
	global_atomic_add v4, v5, s[6:7]
	global_atomic_add v4, v5, s[6:7] offset:256
	global_atomic_add v4, v5, s[6:7] offset:512
	global_atomic_add v4, v5, s[6:7] offset:768
	global_atomic_add v4, v5, s[6:7] offset:1024
	global_atomic_add v4, v5, s[6:7] offset:1280
	global_atomic_add v4, v5, s[6:7] offset:1536
	global_atomic_add v4, v5, s[6:7] offset:1792
	global_atomic_add v4, v5, s[6:7] offset:2048
	global_atomic_add v4, v5, s[6:7] offset:2304
	global_atomic_add v4, v5, s[6:7] offset:2560
	global_atomic_add v4, v5, s[6:7] offset:2816
	global_atomic_add v4, v5, s[6:7] offset:3072
	global_atomic_add v4, v5, s[6:7] offset:3328
	global_atomic_add v4, v5, s[6:7] offset:3584
	global_atomic_add v4, v5, s[6:7] offset:3840
	s_branch .Lxb_done_0

.LBB0_434:
	s_cmp_gt_i32 s83, 4
	s_cselect_b64 s[0:1], -1, 0
	s_and_b64 s[4:5], s[6:7], s[0:1]
	s_andn2_b64 vcc, exec, s[4:5]
	s_cbranch_vccnz .LBB0_488
	s_waitcnt vmcnt(0)
	s_waitcnt vmcnt(0)
	s_barrier
	s_and_saveexec_b64 s[4:5], s[94:95]
	s_cbranch_execz .LBB0_487
	v_readlane_b32 s9, v255, 63
	s_nop 0
	s_cmp_eq_u32 s9, 0
	s_cbranch_scc1 .Lxb_loc_3
	buffer_wbl2 sc1
	s_waitcnt vmcnt(0)
.Lxb_loc_3:
	v_mov_b32_e32 v1, 0x23ff0
	ds_read_b32 v2, v1
	ds_read_b32 v3, v1 offset:4
	s_add_u32 s6, s80, 0x2380000
	s_addc_u32 s7, s81, 0
	s_lshl_b32 s8, s87, 8
	s_add_i32 s9, s8, 0x1400
	s_add_i32 s8, s8, 0x2400
	v_mov_b32_e32 v4, s9
	v_mov_b32_e32 v5, 1
	global_atomic_add v6, v4, v5, s[6:7] sc0
	buffer_inv sc1
	s_waitcnt vmcnt(0) lgkmcnt(0)
	v_readfirstlane_b32 s10, v6
	v_readfirstlane_b32 s11, v2
	v_readfirstlane_b32 s16, v3
	s_add_i32 s10, s10, 1
	s_mul_i32 s11, s11, 4
	s_cmp_lg_u32 s10, s11
	s_cbranch_scc1 .Lxb_nl_3
	v_readlane_b32 s9, v255, 63
	s_nop 0
	s_cmp_lg_u32 s9, 0
	s_cbranch_scc1 .Lxb_glob_3
	v_mov_b32_e32 v4, s8
	global_atomic_add v4, v5, s[6:7]
	s_branch .Lxb_done_3
.Lxb_glob_3:
	v_mov_b32_e32 v4, 0x3400
	global_atomic_add v6, v4, v5, s[6:7] sc0
	s_waitcnt vmcnt(0)
	v_readfirstlane_b32 s10, v6
	s_add_i32 s10, s10, 1
	s_mul_i32 s16, s16, 4
	s_cmp_lg_u32 s10, s16
	s_cbranch_scc1 .Lxb_nl_3
	v_mov_b32_e32 v4, 0x2400
	global_atomic_add v4, v5, s[6:7]
	global_atomic_add v4, v5, s[6:7] offset:256
	global_atomic_add v4, v5, s[6:7] offset:512
	global_atomic_add v4, v5, s[6:7] offset:768
	global_atomic_add v4, v5, s[6:7] offset:1024
	global_atomic_add v4, v5, s[6:7] offset:1280
	global_atomic_add v4, v5, s[6:7] offset:1536
	global_atomic_add v4, v5, s[6:7] offset:1792
	global_atomic_add v4, v5, s[6:7] offset:2048
	global_atomic_add v4, v5, s[6:7] offset:2304
	global_atomic_add v4, v5, s[6:7] offset:2560
	global_atomic_add v4, v5, s[6:7] offset:2816
	global_atomic_add v4, v5, s[6:7] offset:3072
	global_atomic_add v4, v5, s[6:7] offset:3328
	global_atomic_add v4, v5, s[6:7] offset:3584
	global_atomic_add v4, v5, s[6:7] offset:3840
	s_branch .Lxb_done_3

.LBB0_529:
	s_cmp_gt_i32 s83, 5
	s_cselect_b64 s[0:1], -1, 0
	s_and_b64 s[4:5], s[16:17], s[0:1]
	s_andn2_b64 vcc, exec, s[4:5]
	s_cbranch_vccnz .LBB0_583
	s_waitcnt vmcnt(0)
	s_waitcnt vmcnt(0) lgkmcnt(0)
	s_barrier
	s_and_saveexec_b64 s[4:5], s[94:95]
	s_cbranch_execz .LBB0_582
	v_readlane_b32 s9, v255, 63
	s_nop 0
	s_cmp_eq_u32 s9, 0
	s_cbranch_scc1 .Lxb_loc_4
	buffer_wbl2 sc1
	s_waitcnt vmcnt(0)
.Lxb_loc_4:
	v_mov_b32_e32 v1, 0x23ff0
	ds_read_b32 v2, v1
	ds_read_b32 v3, v1 offset:4
	s_add_u32 s6, s80, 0x2380000
	s_addc_u32 s7, s81, 0
	s_lshl_b32 s8, s87, 8
	s_add_i32 s9, s8, 0x1400
	s_add_i32 s8, s8, 0x2400
	v_mov_b32_e32 v4, s9
	v_mov_b32_e32 v5, 1
	global_atomic_add v6, v4, v5, s[6:7] sc0
	buffer_inv sc1
	s_waitcnt vmcnt(0) lgkmcnt(0)
	v_readfirstlane_b32 s10, v6
	v_readfirstlane_b32 s11, v2
	v_readfirstlane_b32 s16, v3
	s_add_i32 s10, s10, 1
	s_mul_i32 s11, s11, 5
	s_cmp_lg_u32 s10, s11
	s_cbranch_scc1 .Lxb_nl_4
	v_mov_b32_e32 v4, 0x3400
	global_atomic_add v6, v4, v5, s[6:7] sc0
	s_waitcnt vmcnt(0)
	v_readfirstlane_b32 s10, v6
	s_add_i32 s10, s10, 1
	v_readlane_b32 s9, v255, 63
	s_nop 0
	s_cmp_eq_u32 s9, 0
	s_cselect_b32 s9, 4, 5
	s_mul_i32 s16, s16, s9
	s_cmp_lg_u32 s10, s16
	s_cbranch_scc1 .Lxb_nl_4
	v_mov_b32_e32 v4, 0x2400
	global_atomic_add v4, v5, s[6:7]
	global_atomic_add v4, v5, s[6:7] offset:256
	global_atomic_add v4, v5, s[6:7] offset:512
	global_atomic_add v4, v5, s[6:7] offset:768
	global_atomic_add v4, v5, s[6:7] offset:1024
	global_atomic_add v4, v5, s[6:7] offset:1280
	global_atomic_add v4, v5, s[6:7] offset:1536
	global_atomic_add v4, v5, s[6:7] offset:1792
	global_atomic_add v4, v5, s[6:7] offset:2048
	global_atomic_add v4, v5, s[6:7] offset:2304
	global_atomic_add v4, v5, s[6:7] offset:2560
	global_atomic_add v4, v5, s[6:7] offset:2816
	global_atomic_add v4, v5, s[6:7] offset:3072
	global_atomic_add v4, v5, s[6:7] offset:3328
	global_atomic_add v4, v5, s[6:7] offset:3584
	global_atomic_add v4, v5, s[6:7] offset:3840
	s_branch .Lxb_done_4

.LBB0_612:
	s_cmp_gt_i32 s83, 6
	s_cselect_b64 s[0:1], -1, 0
	s_and_b64 s[4:5], s[6:7], s[0:1]
	s_andn2_b64 vcc, exec, s[4:5]
	s_cbranch_vccnz .LBB0_666
	s_waitcnt vmcnt(0)
	s_waitcnt vmcnt(0) lgkmcnt(0)
	s_barrier
	s_and_saveexec_b64 s[4:5], s[94:95]
	s_cbranch_execz .LBB0_665
	v_mov_b32_e32 v1, 0x23ff0
	ds_read_b32 v2, v1
	ds_read_b32 v3, v1 offset:4
	s_add_u32 s6, s80, 0x2380000
	s_addc_u32 s7, s81, 0
	s_lshl_b32 s8, s87, 8
	s_add_i32 s9, s8, 0x1400
	s_add_i32 s8, s8, 0x2400
	v_mov_b32_e32 v4, s9
	v_mov_b32_e32 v5, 1
	global_atomic_add v6, v4, v5, s[6:7] sc0
	buffer_inv sc1
	s_waitcnt vmcnt(0) lgkmcnt(0)
	v_readfirstlane_b32 s10, v6
	v_readfirstlane_b32 s11, v2
	v_readfirstlane_b32 s16, v3
	s_add_i32 s10, s10, 1
	s_mul_i32 s11, s11, 6
	s_cmp_lg_u32 s10, s11
	s_cbranch_scc1 .Lxb_nl_5
	v_readlane_b32 s9, v255, 63
	s_nop 0
	s_cmp_lg_u32 s9, 0
	s_cbranch_scc1 .Lxb_glob_5
	v_mov_b32_e32 v4, s8
	global_atomic_add v4, v5, s[6:7]
	s_branch .Lxb_done_5
.Lxb_glob_5:
	v_mov_b32_e32 v4, 0x3400
	global_atomic_add v6, v4, v5, s[6:7] sc0
	s_waitcnt vmcnt(0)
	v_readfirstlane_b32 s10, v6
	s_add_i32 s10, s10, 1
	s_mul_i32 s16, s16, 6
	s_cmp_lg_u32 s10, s16
	s_cbranch_scc1 .Lxb_nl_5
	v_mov_b32_e32 v4, 0x2400
	global_atomic_add v4, v5, s[6:7]
	global_atomic_add v4, v5, s[6:7] offset:256
	global_atomic_add v4, v5, s[6:7] offset:512
	global_atomic_add v4, v5, s[6:7] offset:768
	global_atomic_add v4, v5, s[6:7] offset:1024
	global_atomic_add v4, v5, s[6:7] offset:1280
	global_atomic_add v4, v5, s[6:7] offset:1536
	global_atomic_add v4, v5, s[6:7] offset:1792
	global_atomic_add v4, v5, s[6:7] offset:2048
	global_atomic_add v4, v5, s[6:7] offset:2304
	global_atomic_add v4, v5, s[6:7] offset:2560
	global_atomic_add v4, v5, s[6:7] offset:2816
	global_atomic_add v4, v5, s[6:7] offset:3072
	global_atomic_add v4, v5, s[6:7] offset:3328
	global_atomic_add v4, v5, s[6:7] offset:3584
	global_atomic_add v4, v5, s[6:7] offset:3840
	s_branch .Lxb_done_5
